# drop denormal-input guards around rsqrt where argument is x*c+1e-6 (17 sites, A1/attention epilogues)
# speedup vs baseline: 1.0025x; 1.0003x over previous
.LBB0_59:
	v_lshlrev_b32_e32 v16, 16, v140
	v_fma_f32 v17, v32, v40, v138
	v_mul_f32_e32 v32, v17, v16
	v_and_b32_e32 v16, 0xffff0000, v140
	v_fma_f32 v17, v33, v41, v138
	v_mul_f32_e32 v33, v17, v16
	v_lshlrev_b32_e32 v16, 16, v141
	v_fma_f32 v17, v34, v42, v138
	v_mul_f32_e32 v34, v17, v16
	v_and_b32_e32 v16, 0xffff0000, v141
	v_fma_f32 v17, v35, v43, v138
	v_mul_f32_e32 v35, v17, v16
	v_mul_f32_e32 v16, v33, v33
	v_mul_f32_e32 v17, v34, v34
	v_fmac_f32_e32 v16, v32, v32
	v_fmac_f32_e32 v17, v35, v35
	v_add_f32_e32 v16, v16, v17
	v_lshlrev_b32_e32 v17, 16, v136
	v_fma_f32 v18, v36, v52, v138
	v_mul_f32_e32 v36, v18, v17
	v_and_b32_e32 v17, 0xffff0000, v136
	v_fma_f32 v18, v37, v53, v138
	v_mul_f32_e32 v37, v18, v17
	v_lshlrev_b32_e32 v17, 16, v137
	v_fma_f32 v18, v38, v54, v138
	v_mul_f32_e32 v38, v18, v17
	v_and_b32_e32 v17, 0xffff0000, v137
	v_fma_f32 v18, v39, v55, v138
	v_mul_f32_e32 v39, v18, v17
	v_mul_f32_e32 v17, v37, v37
	v_mul_f32_e32 v18, v38, v38
	v_fmac_f32_e32 v17, v36, v36
	v_fmac_f32_e32 v18, v39, v39
	v_add_f32_e32 v17, v17, v18
	v_add_f32_e32 v16, v16, v17
	v_lshlrev_b32_e32 v17, 16, v134
	v_fma_f32 v18, v44, v60, v138
	v_mul_f32_e32 v40, v18, v17
	v_and_b32_e32 v17, 0xffff0000, v134
	v_fma_f32 v18, v45, v61, v138
	v_mul_f32_e32 v41, v18, v17
	v_lshlrev_b32_e32 v17, 16, v135
	v_fma_f32 v18, v46, v62, v138
	v_mul_f32_e32 v42, v18, v17
	v_and_b32_e32 v17, 0xffff0000, v135
	v_fma_f32 v18, v47, v63, v138
	v_mul_f32_e32 v43, v18, v17
	v_mul_f32_e32 v17, v41, v41
	v_mul_f32_e32 v18, v42, v42
	v_fmac_f32_e32 v17, v40, v40
	v_fmac_f32_e32 v18, v43, v43
	v_add_f32_e32 v17, v17, v18
	v_add_f32_e32 v16, v16, v17
	v_lshlrev_b32_e32 v17, 16, v132
	v_fma_f32 v18, v48, v68, v138
	v_mul_f32_e32 v44, v18, v17
	v_and_b32_e32 v17, 0xffff0000, v132
	v_fma_f32 v18, v49, v69, v138
	v_mul_f32_e32 v45, v18, v17
	v_lshlrev_b32_e32 v17, 16, v133
	v_fma_f32 v18, v50, v70, v138
	v_mul_f32_e32 v46, v18, v17
	v_and_b32_e32 v17, 0xffff0000, v133
	v_fma_f32 v18, v51, v71, v138
	v_mul_f32_e32 v47, v18, v17
	v_mul_f32_e32 v17, v45, v45
	v_mul_f32_e32 v18, v46, v46
	v_fmac_f32_e32 v17, v44, v44
	v_fmac_f32_e32 v18, v47, v47
	v_add_f32_e32 v17, v17, v18
	v_add_f32_e32 v16, v16, v17
	v_lshlrev_b32_e32 v17, 16, v130
	v_fma_f32 v18, v56, v76, v138
	v_mul_f32_e32 v48, v18, v17
	v_and_b32_e32 v17, 0xffff0000, v130
	v_fma_f32 v18, v57, v77, v138
	v_mul_f32_e32 v49, v18, v17
	v_lshlrev_b32_e32 v17, 16, v131
	v_fma_f32 v18, v58, v78, v138
	v_mul_f32_e32 v50, v18, v17
	v_and_b32_e32 v17, 0xffff0000, v131
	v_fma_f32 v18, v59, v79, v138
	v_mul_f32_e32 v51, v18, v17
	v_mul_f32_e32 v17, v49, v49
	v_mul_f32_e32 v18, v50, v50
	v_fmac_f32_e32 v17, v48, v48
	v_fmac_f32_e32 v18, v51, v51
	v_add_f32_e32 v17, v17, v18
	v_add_f32_e32 v16, v16, v17
	v_lshlrev_b32_e32 v17, 16, v128
	v_fma_f32 v18, v64, v80, v138
	v_mul_f32_e32 v52, v18, v17
	v_and_b32_e32 v17, 0xffff0000, v128
	v_fma_f32 v18, v65, v81, v138
	v_mul_f32_e32 v53, v18, v17
	v_lshlrev_b32_e32 v17, 16, v129
	v_fma_f32 v18, v66, v82, v138
	v_mul_f32_e32 v54, v18, v17
	v_and_b32_e32 v17, 0xffff0000, v129
	v_fma_f32 v18, v67, v83, v138
	v_mul_f32_e32 v55, v18, v17
	v_mul_f32_e32 v17, v53, v53
	v_mul_f32_e32 v18, v54, v54
	v_fmac_f32_e32 v17, v52, v52
	v_fmac_f32_e32 v18, v55, v55
	v_add_f32_e32 v17, v17, v18
	v_add_f32_e32 v16, v16, v17
	v_lshlrev_b32_e32 v17, 16, v126
	s_waitcnt lgkmcnt(0)
	v_fma_f32 v18, v72, v28, v138
	v_mul_f32_e32 v28, v18, v17
	v_and_b32_e32 v17, 0xffff0000, v126
	v_fma_f32 v18, v73, v29, v138
	v_mul_f32_e32 v29, v18, v17
	v_lshlrev_b32_e32 v17, 16, v127
	v_fma_f32 v18, v74, v30, v138
	v_mul_f32_e32 v30, v18, v17
	v_and_b32_e32 v17, 0xffff0000, v127
	v_fma_f32 v18, v75, v31, v138
	v_mul_f32_e32 v31, v18, v17
	v_mul_f32_e32 v17, v29, v29
	v_mul_f32_e32 v18, v30, v30
	v_fmac_f32_e32 v17, v28, v28
	v_fmac_f32_e32 v18, v31, v31
	v_add_f32_e32 v17, v17, v18
	v_add_f32_e32 v21, v16, v17
	ds_read_b128 v[16:19], v89 offset:448
	v_and_b32_e32 v22, 0xffff0000, v124
	v_lshlrev_b32_e32 v23, 16, v125
	s_and_b32 s27, s33, 0xffffff80
	v_add_u32_e32 v20, s27, v102
	s_waitcnt lgkmcnt(0)
	v_pk_mul_f32 v[18:19], v[26:27], v[18:19]
	v_pk_mul_f32 v[24:25], v[24:25], v[16:17]
	v_lshl_add_u32 v27, s36, 2, v143
	v_pk_mov_b32 v[16:17], v[24:25], v[18:19] op_sel:[1,0]
	v_mov_b32_e32 v25, v19
	v_pk_add_f32 v[16:17], v[138:139], v[16:17] op_sel_hi:[0,1]
	v_pk_mul_f32 v[16:17], v[16:17], v[22:23]
	v_lshlrev_b32_e32 v22, 16, v124
	v_and_b32_e32 v23, 0xffff0000, v125
	v_pk_add_f32 v[18:19], v[138:139], v[24:25] op_sel_hi:[0,1]
	v_pk_mul_f32 v[18:19], v[18:19], v[22:23]
	v_pk_mul_f32 v[22:23], v[16:17], v[16:17]
	s_lshl_b32 s98, s36, 1
	v_pk_fma_f32 v[22:23], v[18:19], v[18:19], v[22:23]
	v_lshlrev_b32_e32 v144, 1, v85
	v_add_f32_e32 v22, v22, v23
	v_and_b32_e32 v23, 64, v214
	v_add_f32_e32 v21, v21, v22
	v_xor_b32_e32 v22, 16, v214
	v_add_u32_e32 v23, 64, v23
	v_cmp_lt_i32_e32 vcc, v22, v23
	s_xor_b32 s35, s35, 1
	s_add_i32 s33, s33, 32
	v_cndmask_b32_e32 v22, v214, v22, vcc
	v_lshlrev_b32_e32 v22, 2, v22
	ds_bpermute_b32 v22, v22, v21
	s_addk_i32 s34, 0x80
	s_waitcnt vmcnt(0)
	v_mov_b64_e32 v[140:141], v[120:121]
	v_mov_b64_e32 v[136:137], v[118:119]
	v_mov_b64_e32 v[134:135], v[116:117]
	s_waitcnt lgkmcnt(0)
	v_add_f32_e32 v21, v21, v22
	v_xor_b32_e32 v22, 32, v214
	v_cmp_lt_i32_e32 vcc, v22, v23
	v_mov_b64_e32 v[132:133], v[114:115]
	v_mov_b64_e32 v[130:131], v[112:113]
	v_cndmask_b32_e32 v22, v214, v22, vcc
	v_lshlrev_b32_e32 v22, 2, v22
	ds_bpermute_b32 v22, v22, v21
	v_mov_b64_e32 v[128:129], v[110:111]
	v_mov_b64_e32 v[126:127], v[108:109]
	v_mov_b64_e32 v[124:125], v[106:107]
	s_waitcnt lgkmcnt(0)
	v_add_f32_e32 v21, v21, v22
	v_fmamk_f32 v21, v21, 0x3c000000, v210
	s_nop 0
	v_rsq_f32_e32 v21, v21
	s_nop 0
	v_mov_b32_e32 v26, v21
	ds_read_b128 v[22:25], v27
	v_mul_f32_e32 v32, v32, v26
	v_ashrrev_i32_e32 v21, 31, v20
	v_lshlrev_b64 v[20:21], 11, v[20:21]
	v_lshl_add_u64 v[20:21], s[44:45], 0, v[20:21]
	s_waitcnt lgkmcnt(0)
	v_mul_f32_e32 v22, v22, v32
	v_mul_f32_e32 v32, v33, v26
	v_mul_f32_e32 v23, v23, v32
	v_cvt_pk_bf16_f32 v22, v22, v23
	v_mul_f32_e32 v23, v34, v26
	v_mul_f32_e32 v23, v24, v23
	v_mul_f32_e32 v24, v35, v26
	v_lshl_add_u64 v[20:21], v[20:21], 0, s[98:99]
	v_mul_f32_e32 v24, v25, v24
	v_cvt_pk_bf16_f32 v23, v23, v24
	v_lshl_add_u64 v[24:25], v[20:21], 0, v[144:145]
	global_store_dwordx2 v[24:25], v[22:23], off
	ds_read_b128 v[20:23], v27 offset:64
	v_mul_f32_e32 v32, v36, v26
	v_mul_f32_e32 v28, v28, v26
	v_mul_f32_e32 v18, v18, v26
	v_mul_f32_e32 v16, v16, v26
	s_waitcnt lgkmcnt(0)
	v_mul_f32_e32 v20, v20, v32
	v_mul_f32_e32 v32, v37, v26
	v_mul_f32_e32 v21, v21, v32
	v_cvt_pk_bf16_f32 v20, v20, v21
	v_mul_f32_e32 v21, v38, v26
	v_mul_f32_e32 v21, v22, v21
	v_mul_f32_e32 v22, v39, v26
	v_mul_f32_e32 v22, v23, v22
	v_cvt_pk_bf16_f32 v21, v21, v22
	global_store_dwordx2 v[24:25], v[20:21], off offset:32
	ds_read_b128 v[20:23], v27 offset:128
	v_mul_f32_e32 v32, v40, v26
	v_mul_f32_e32 v17, v17, v26
	s_and_b64 vcc, exec, s[46:47]
	s_waitcnt lgkmcnt(0)
	v_mul_f32_e32 v20, v20, v32
	v_mul_f32_e32 v32, v41, v26
	v_mul_f32_e32 v21, v21, v32
	v_cvt_pk_bf16_f32 v20, v20, v21
	v_mul_f32_e32 v21, v42, v26
	v_mul_f32_e32 v21, v22, v21
	v_mul_f32_e32 v22, v43, v26
	v_mul_f32_e32 v22, v23, v22
	v_cvt_pk_bf16_f32 v21, v21, v22
	global_store_dwordx2 v[24:25], v[20:21], off offset:64
	ds_read_b128 v[20:23], v27 offset:192
	v_mul_f32_e32 v32, v44, v26
	s_waitcnt lgkmcnt(0)
	v_mul_f32_e32 v20, v20, v32
	v_mul_f32_e32 v32, v45, v26
	v_mul_f32_e32 v21, v21, v32
	v_cvt_pk_bf16_f32 v20, v20, v21
	v_mul_f32_e32 v21, v46, v26
	v_mul_f32_e32 v21, v22, v21
	v_mul_f32_e32 v22, v47, v26
	v_mul_f32_e32 v22, v23, v22
	v_cvt_pk_bf16_f32 v21, v21, v22
	global_store_dwordx2 v[24:25], v[20:21], off offset:96
	ds_read_b128 v[20:23], v27 offset:256
	v_mul_f32_e32 v32, v48, v26
	s_waitcnt lgkmcnt(0)
	v_mul_f32_e32 v20, v32, v20
	v_mul_f32_e32 v32, v49, v26
	v_mul_f32_e32 v21, v32, v21
	v_cvt_pk_bf16_f32 v20, v20, v21
	v_mul_f32_e32 v21, v50, v26
	v_mul_f32_e32 v21, v21, v22
	v_mul_f32_e32 v22, v51, v26
	v_mul_f32_e32 v22, v22, v23
	v_cvt_pk_bf16_f32 v21, v21, v22
	global_store_dwordx2 v[24:25], v[20:21], off offset:128
	ds_read_b128 v[20:23], v27 offset:320
	v_mul_f32_e32 v32, v52, v26
	s_waitcnt lgkmcnt(0)
	v_mul_f32_e32 v20, v32, v20
	v_mul_f32_e32 v32, v53, v26
	v_mul_f32_e32 v21, v32, v21
	v_cvt_pk_bf16_f32 v20, v20, v21
	v_mul_f32_e32 v21, v54, v26
	v_mul_f32_e32 v21, v21, v22
	v_mul_f32_e32 v22, v55, v26
	v_mul_f32_e32 v22, v22, v23
	v_cvt_pk_bf16_f32 v21, v21, v22
	global_store_dwordx2 v[24:25], v[20:21], off offset:160
	ds_read_b128 v[20:23], v27 offset:384
	v_mov_b64_e32 v[32:33], v[122:123]
	s_waitcnt lgkmcnt(0)
	v_mul_f32_e32 v20, v28, v20
	v_mul_f32_e32 v28, v29, v26
	v_mul_f32_e32 v21, v28, v21
	v_cvt_pk_bf16_f32 v20, v20, v21
	v_mul_f32_e32 v21, v30, v26
	v_mul_f32_e32 v21, v21, v22
	v_mul_f32_e32 v22, v31, v26
	v_mul_f32_e32 v22, v22, v23
	v_cvt_pk_bf16_f32 v21, v21, v22
	global_store_dwordx2 v[24:25], v[20:21], off offset:192
	ds_read_b128 v[20:23], v27 offset:448
	v_mov_b64_e32 v[30:31], v[6:7]
	v_mov_b64_e32 v[28:29], v[4:5]
	s_waitcnt lgkmcnt(0)
	v_mul_f32_e32 v18, v18, v20
	v_mul_f32_e32 v16, v16, v21
	v_cvt_pk_bf16_f32 v16, v18, v16
	v_mul_f32_e32 v17, v17, v22
	v_mul_f32_e32 v18, v19, v26
	v_mul_f32_e32 v18, v18, v23
	v_cvt_pk_bf16_f32 v17, v17, v18
	global_store_dwordx2 v[24:25], v[16:17], off offset:224
	s_waitcnt vmcnt(8)
	v_mov_b64_e32 v[26:27], v[2:3]
	v_mov_b64_e32 v[22:23], v[10:11]
	v_mov_b64_e32 v[18:19], v[14:15]
	v_mov_b64_e32 v[24:25], v[0:1]
	v_mov_b64_e32 v[20:21], v[8:9]
	v_mov_b64_e32 v[16:17], v[12:13]
	s_barrier
	s_cbranch_vccnz .LBB0_103

.LBB0_326:
	s_add_u32 s27, s52, 0xfffc0080
	s_addc_u32 s35, s53, -1
	s_add_i32 s36, 0, 0x10000
	v_add_u32_e32 v140, s36, v216
	ds_read_b128 v[128:131], v140
	ds_read_b128 v[132:135], v140 offset:1024
	ds_read_b128 v[136:139], v140 offset:2048
	ds_read_b128 v[140:143], v140 offset:3072
	s_cmp_eq_u32 s34, 12
	s_cselect_b32 s75, s1, s35
	s_cselect_b32 s74, s11, s27
	s_cselect_b32 s73, s25, s33
	s_cselect_b32 s72, s30, s31
	v_lshl_add_u64 v[168:169], s[52:53], 0, v[152:153]
	s_add_i32 m0, s83, 0xc000
	ds_read_b128 v[156:159], v217
	ds_read_b128 v[160:163], v217 offset:1024
	ds_read_b128 v[164:167], v217 offset:2048
	ds_read_b128 v[188:191], v217 offset:3072
	ds_read_b128 v[192:195], v217 offset:4096
	ds_read_b128 v[196:199], v217 offset:5120
	ds_read_b128 v[200:203], v217 offset:6144
	ds_read_b128 v[204:207], v217 offset:7168
	global_load_lds_dwordx4 v[168:169], off
	v_lshl_add_u64 v[168:169], s[52:53], 0, v[154:155]
	s_add_i32 m0, s83, 0xe000
	s_nop 0
	global_load_lds_dwordx4 v[168:169], off
	s_waitcnt lgkmcnt(8)
	s_barrier
	s_waitcnt lgkmcnt(0)
	s_setprio 1
	s_waitcnt lgkmcnt(0)
	v_mfma_f32_16x16x32_bf16 v[124:127], v[128:131], v[156:159], v[124:127]
	v_mfma_f32_16x16x32_bf16 v[120:123], v[136:139], v[156:159], v[120:123]
	v_mfma_f32_16x16x32_bf16 v[108:111], v[128:131], v[164:167], v[108:111]
	v_mfma_f32_16x16x32_bf16 v[104:107], v[136:139], v[164:167], v[104:107]
	v_mfma_f32_16x16x32_bf16 v[92:95], v[128:131], v[192:195], v[92:95]
	v_mfma_f32_16x16x32_bf16 v[88:91], v[136:139], v[192:195], v[88:91]
	v_mfma_f32_16x16x32_bf16 v[76:79], v[128:131], v[200:203], v[76:79]
	v_mfma_f32_16x16x32_bf16 v[72:75], v[136:139], v[200:203], v[72:75]
	v_mfma_f32_16x16x32_bf16 v[124:127], v[132:135], v[160:163], v[124:127]
	v_mfma_f32_16x16x32_bf16 v[120:123], v[140:143], v[160:163], v[120:123]
	v_mfma_f32_16x16x32_bf16 v[108:111], v[132:135], v[188:191], v[108:111]
	v_mfma_f32_16x16x32_bf16 v[104:107], v[140:143], v[188:191], v[104:107]
	v_mfma_f32_16x16x32_bf16 v[92:95], v[132:135], v[196:199], v[92:95]
	v_mfma_f32_16x16x32_bf16 v[88:91], v[140:143], v[196:199], v[88:91]
	v_mfma_f32_16x16x32_bf16 v[76:79], v[132:135], v[204:207], v[76:79]
	v_mfma_f32_16x16x32_bf16 v[72:75], v[140:143], v[204:207], v[72:75]
	s_setprio 0
	s_barrier
	s_add_i32 s27, 0, 0x14000
	s_add_i32 s35, s36, s81
	v_add_u32_e32 v144, s27, v216
	v_lshl_add_u64 v[168:169], s[72:73], 0, v[148:149]
	s_mov_b32 m0, s35
	ds_read_b128 v[220:223], v144
	ds_read_b128 v[228:231], v144 offset:1024
	ds_read_b128 v[232:235], v144 offset:2048
	ds_read_b128 v[236:239], v144 offset:3072
	global_load_lds_dwordx4 v[168:169], off
	v_lshl_add_u64 v[176:177], s[72:73], 0, v[146:147]
	s_add_i32 m0, s35, 0x2000
	s_nop 0
	global_load_lds_dwordx4 v[176:177], off
	s_barrier
	s_waitcnt lgkmcnt(0)
	s_setprio 1
	s_waitcnt lgkmcnt(0)
	v_mfma_f32_16x16x32_bf16 v[116:119], v[220:223], v[156:159], v[116:119]
	v_mfma_f32_16x16x32_bf16 v[112:115], v[232:235], v[156:159], v[112:115]
	v_mfma_f32_16x16x32_bf16 v[100:103], v[220:223], v[164:167], v[100:103]
	v_mfma_f32_16x16x32_bf16 v[96:99], v[232:235], v[164:167], v[96:99]
	v_mfma_f32_16x16x32_bf16 v[84:87], v[220:223], v[192:195], v[84:87]
	v_mfma_f32_16x16x32_bf16 v[80:83], v[232:235], v[192:195], v[80:83]
	v_mfma_f32_16x16x32_bf16 v[68:71], v[220:223], v[200:203], v[68:71]
	v_mfma_f32_16x16x32_bf16 v[64:67], v[232:235], v[200:203], v[64:67]
	v_mfma_f32_16x16x32_bf16 v[116:119], v[228:231], v[160:163], v[116:119]
	v_mfma_f32_16x16x32_bf16 v[112:115], v[236:239], v[160:163], v[112:115]
	v_mfma_f32_16x16x32_bf16 v[100:103], v[228:231], v[188:191], v[100:103]
	v_mfma_f32_16x16x32_bf16 v[96:99], v[236:239], v[188:191], v[96:99]
	v_mfma_f32_16x16x32_bf16 v[84:87], v[228:231], v[196:199], v[84:87]
	v_mfma_f32_16x16x32_bf16 v[80:83], v[236:239], v[196:199], v[80:83]
	v_mfma_f32_16x16x32_bf16 v[68:71], v[228:231], v[204:207], v[68:71]
	v_mfma_f32_16x16x32_bf16 v[64:67], v[236:239], v[204:207], v[64:67]
	s_setprio 0
	s_mov_b32 m0, s83
	v_lshl_add_u64 v[224:225], s[74:75], 0, v[148:149]
	s_barrier
	ds_read_b128 v[156:159], v217 offset:16384
	ds_read_b128 v[160:163], v217 offset:17408
	ds_read_b128 v[164:167], v217 offset:18432
	ds_read_b128 v[188:191], v217 offset:19456
	ds_read_b128 v[192:195], v217 offset:20480
	ds_read_b128 v[196:199], v217 offset:21504
	ds_read_b128 v[200:203], v217 offset:22528
	ds_read_b128 v[204:207], v217 offset:23552
	global_load_lds_dwordx4 v[224:225], off
	v_lshl_add_u64 v[240:241], s[74:75], 0, v[146:147]
	s_mov_b32 m0, s84
	s_nop 0
	global_load_lds_dwordx4 v[240:241], off
	s_barrier
	s_waitcnt lgkmcnt(0)
	s_setprio 1
	s_waitcnt lgkmcnt(0)
	v_mfma_f32_16x16x32_bf16 v[60:63], v[128:131], v[156:159], v[60:63]
	v_mfma_f32_16x16x32_bf16 v[56:59], v[136:139], v[156:159], v[56:59]
	v_mfma_f32_16x16x32_bf16 v[44:47], v[128:131], v[164:167], v[44:47]
	v_mfma_f32_16x16x32_bf16 v[40:43], v[136:139], v[164:167], v[40:43]
	v_mfma_f32_16x16x32_bf16 v[28:31], v[128:131], v[192:195], v[28:31]
	v_mfma_f32_16x16x32_bf16 v[24:27], v[136:139], v[192:195], v[24:27]
	v_mfma_f32_16x16x32_bf16 v[12:15], v[128:131], v[200:203], v[12:15]
	v_mfma_f32_16x16x32_bf16 v[8:11], v[136:139], v[200:203], v[8:11]
	v_mfma_f32_16x16x32_bf16 v[60:63], v[132:135], v[160:163], v[60:63]
	v_mfma_f32_16x16x32_bf16 v[56:59], v[140:143], v[160:163], v[56:59]
	v_mfma_f32_16x16x32_bf16 v[44:47], v[132:135], v[188:191], v[44:47]
	v_mfma_f32_16x16x32_bf16 v[40:43], v[140:143], v[188:191], v[40:43]
	v_mfma_f32_16x16x32_bf16 v[28:31], v[132:135], v[196:199], v[28:31]
	v_mfma_f32_16x16x32_bf16 v[24:27], v[140:143], v[196:199], v[24:27]
	v_mfma_f32_16x16x32_bf16 v[12:15], v[132:135], v[204:207], v[12:15]
	v_mfma_f32_16x16x32_bf16 v[8:11], v[140:143], v[204:207], v[8:11]
	s_setprio 0
	s_barrier
	s_add_u32 s36, s72, 0x40000
	s_addc_u32 s37, s73, 0
	s_add_i32 s27, s27, s81
	v_lshl_add_u64 v[128:129], s[36:37], 0, v[148:149]
	s_mov_b32 m0, s27
	s_nop 0
	global_load_lds_dwordx4 v[128:129], off
	v_lshl_add_u64 v[128:129], s[36:37], 0, v[146:147]
	s_add_i32 m0, s27, 0x2000
	s_nop 0
	global_load_lds_dwordx4 v[128:129], off
	s_waitcnt vmcnt(6)
	s_barrier
	s_setprio 1
	v_mfma_f32_16x16x32_bf16 v[52:55], v[220:223], v[156:159], v[52:55]
	v_mfma_f32_16x16x32_bf16 v[48:51], v[232:235], v[156:159], v[48:51]
	v_mfma_f32_16x16x32_bf16 v[36:39], v[220:223], v[164:167], v[36:39]
	v_mfma_f32_16x16x32_bf16 v[32:35], v[232:235], v[164:167], v[32:35]
	v_mfma_f32_16x16x32_bf16 v[20:23], v[220:223], v[192:195], v[20:23]
	v_mfma_f32_16x16x32_bf16 v[16:19], v[232:235], v[192:195], v[16:19]
	v_mfma_f32_16x16x32_bf16 v[4:7], v[220:223], v[200:203], v[4:7]
	v_mfma_f32_16x16x32_bf16 v[0:3], v[232:235], v[200:203], v[0:3]
	v_mfma_f32_16x16x32_bf16 v[52:55], v[228:231], v[160:163], v[52:55]
	v_mfma_f32_16x16x32_bf16 v[48:51], v[236:239], v[160:163], v[48:51]
	v_mfma_f32_16x16x32_bf16 v[36:39], v[228:231], v[188:191], v[36:39]
	v_mfma_f32_16x16x32_bf16 v[32:35], v[236:239], v[188:191], v[32:35]
	v_mfma_f32_16x16x32_bf16 v[20:23], v[228:231], v[196:199], v[20:23]
	v_mfma_f32_16x16x32_bf16 v[16:19], v[236:239], v[196:199], v[16:19]
	v_mfma_f32_16x16x32_bf16 v[4:7], v[228:231], v[204:207], v[4:7]
	v_mfma_f32_16x16x32_bf16 v[0:3], v[236:239], v[204:207], v[0:3]
	s_setprio 0
	s_add_i32 s27, 0, 0x18000
	v_add_u32_e32 v140, s27, v216
	s_barrier
	ds_read_b128 v[128:131], v140
	ds_read_b128 v[132:135], v140 offset:1024
	ds_read_b128 v[136:139], v140 offset:2048
	ds_read_b128 v[140:143], v140 offset:3072
	s_add_u32 s36, s74, 0x40000
	s_addc_u32 s37, s75, 0
	s_mov_b32 m0, s85
	v_lshl_add_u64 v[220:221], s[36:37], 0, v[148:149]
	ds_read_b128 v[156:159], v217 offset:32768
	ds_read_b128 v[160:163], v217 offset:33792
	ds_read_b128 v[164:167], v217 offset:34816
	ds_read_b128 v[188:191], v217 offset:35840
	ds_read_b128 v[192:195], v217 offset:36864
	ds_read_b128 v[196:199], v217 offset:37888
	ds_read_b128 v[200:203], v217 offset:38912
	ds_read_b128 v[204:207], v217 offset:39936
	global_load_lds_dwordx4 v[220:221], off
	v_lshl_add_u64 v[220:221], s[36:37], 0, v[146:147]
	s_mov_b32 m0, s86
	s_nop 0
	global_load_lds_dwordx4 v[220:221], off
	s_waitcnt lgkmcnt(8)
	s_barrier
	s_waitcnt lgkmcnt(0)
	s_setprio 1
	s_waitcnt lgkmcnt(0)
	v_mfma_f32_16x16x32_bf16 v[124:127], v[128:131], v[156:159], v[124:127]
	v_mfma_f32_16x16x32_bf16 v[120:123], v[136:139], v[156:159], v[120:123]
	v_mfma_f32_16x16x32_bf16 v[108:111], v[128:131], v[164:167], v[108:111]
	v_mfma_f32_16x16x32_bf16 v[104:107], v[136:139], v[164:167], v[104:107]
	v_mfma_f32_16x16x32_bf16 v[92:95], v[128:131], v[192:195], v[92:95]
	v_mfma_f32_16x16x32_bf16 v[88:91], v[136:139], v[192:195], v[88:91]
	v_mfma_f32_16x16x32_bf16 v[76:79], v[128:131], v[200:203], v[76:79]
	v_mfma_f32_16x16x32_bf16 v[72:75], v[136:139], v[200:203], v[72:75]
	v_mfma_f32_16x16x32_bf16 v[124:127], v[132:135], v[160:163], v[124:127]
	v_mfma_f32_16x16x32_bf16 v[120:123], v[140:143], v[160:163], v[120:123]
	v_mfma_f32_16x16x32_bf16 v[108:111], v[132:135], v[188:191], v[108:111]
	v_mfma_f32_16x16x32_bf16 v[104:107], v[140:143], v[188:191], v[104:107]
	v_mfma_f32_16x16x32_bf16 v[92:95], v[132:135], v[196:199], v[92:95]
	v_mfma_f32_16x16x32_bf16 v[88:91], v[140:143], v[196:199], v[88:91]
	v_mfma_f32_16x16x32_bf16 v[76:79], v[132:135], v[204:207], v[76:79]
	v_mfma_f32_16x16x32_bf16 v[72:75], v[140:143], v[204:207], v[72:75]
	s_setprio 0
	s_barrier
	s_add_i32 s35, 0, 0x1c000
	s_add_i32 s27, s27, s81
	v_add_u32_e32 v144, s35, v216
	v_lshl_add_u64 v[168:169], v[168:169], 0, s[18:19]
	s_mov_b32 m0, s27
	ds_read_b128 v[220:223], v144
	ds_read_b128 v[228:231], v144 offset:1024
	ds_read_b128 v[232:235], v144 offset:2048
	ds_read_b128 v[236:239], v144 offset:3072
	global_load_lds_dwordx4 v[168:169], off
	v_lshl_add_u64 v[168:169], v[176:177], 0, s[18:19]
	s_add_i32 m0, s27, 0x2000
	s_nop 0
	global_load_lds_dwordx4 v[168:169], off
	s_barrier
	s_waitcnt lgkmcnt(0)
	s_setprio 1
	s_waitcnt lgkmcnt(0)
	v_mfma_f32_16x16x32_bf16 v[116:119], v[220:223], v[156:159], v[116:119]
	v_mfma_f32_16x16x32_bf16 v[112:115], v[232:235], v[156:159], v[112:115]
	v_mfma_f32_16x16x32_bf16 v[100:103], v[220:223], v[164:167], v[100:103]
	v_mfma_f32_16x16x32_bf16 v[96:99], v[232:235], v[164:167], v[96:99]
	v_mfma_f32_16x16x32_bf16 v[84:87], v[220:223], v[192:195], v[84:87]
	v_mfma_f32_16x16x32_bf16 v[80:83], v[232:235], v[192:195], v[80:83]
	v_mfma_f32_16x16x32_bf16 v[68:71], v[220:223], v[200:203], v[68:71]
	v_mfma_f32_16x16x32_bf16 v[64:67], v[232:235], v[200:203], v[64:67]
	v_mfma_f32_16x16x32_bf16 v[116:119], v[228:231], v[160:163], v[116:119]
	v_mfma_f32_16x16x32_bf16 v[112:115], v[236:239], v[160:163], v[112:115]
	v_mfma_f32_16x16x32_bf16 v[100:103], v[228:231], v[188:191], v[100:103]
	v_mfma_f32_16x16x32_bf16 v[96:99], v[236:239], v[188:191], v[96:99]
	v_mfma_f32_16x16x32_bf16 v[84:87], v[228:231], v[196:199], v[84:87]
	v_mfma_f32_16x16x32_bf16 v[80:83], v[236:239], v[196:199], v[80:83]
	v_mfma_f32_16x16x32_bf16 v[68:71], v[228:231], v[204:207], v[68:71]
	v_mfma_f32_16x16x32_bf16 v[64:67], v[236:239], v[204:207], v[64:67]
	s_setprio 0
	s_mov_b32 m0, s87
	v_lshl_add_u64 v[168:169], v[224:225], 0, s[18:19]
	s_barrier
	ds_read_b128 v[156:159], v217 offset:49152
	ds_read_b128 v[160:163], v217 offset:50176
	ds_read_b128 v[164:167], v217 offset:51200
	ds_read_b128 v[188:191], v217 offset:52224
	ds_read_b128 v[192:195], v217 offset:53248
	ds_read_b128 v[196:199], v217 offset:54272
	ds_read_b128 v[200:203], v217 offset:55296
	ds_read_b128 v[204:207], v217 offset:56320
	global_load_lds_dwordx4 v[168:169], off
	v_lshl_add_u64 v[168:169], v[240:241], 0, s[18:19]
	s_mov_b32 m0, s79
	s_nop 0
	global_load_lds_dwordx4 v[168:169], off
	s_barrier
	s_waitcnt lgkmcnt(0)
	s_setprio 1
	s_waitcnt lgkmcnt(0)
	v_mfma_f32_16x16x32_bf16 v[60:63], v[128:131], v[156:159], v[60:63]
	v_mfma_f32_16x16x32_bf16 v[56:59], v[136:139], v[156:159], v[56:59]
	v_mfma_f32_16x16x32_bf16 v[44:47], v[128:131], v[164:167], v[44:47]
	v_mfma_f32_16x16x32_bf16 v[40:43], v[136:139], v[164:167], v[40:43]
	v_mfma_f32_16x16x32_bf16 v[28:31], v[128:131], v[192:195], v[28:31]
	v_mfma_f32_16x16x32_bf16 v[24:27], v[136:139], v[192:195], v[24:27]
	v_mfma_f32_16x16x32_bf16 v[12:15], v[128:131], v[200:203], v[12:15]
	v_mfma_f32_16x16x32_bf16 v[8:11], v[136:139], v[200:203], v[8:11]
	v_mfma_f32_16x16x32_bf16 v[60:63], v[132:135], v[160:163], v[60:63]
	v_mfma_f32_16x16x32_bf16 v[56:59], v[140:143], v[160:163], v[56:59]
	v_mfma_f32_16x16x32_bf16 v[44:47], v[132:135], v[188:191], v[44:47]
	v_mfma_f32_16x16x32_bf16 v[40:43], v[140:143], v[188:191], v[40:43]
	v_mfma_f32_16x16x32_bf16 v[28:31], v[132:135], v[196:199], v[28:31]
	v_mfma_f32_16x16x32_bf16 v[24:27], v[140:143], v[196:199], v[24:27]
	v_mfma_f32_16x16x32_bf16 v[12:15], v[132:135], v[204:207], v[12:15]
	v_mfma_f32_16x16x32_bf16 v[8:11], v[140:143], v[204:207], v[8:11]
	s_setprio 0
	s_barrier
	s_add_u32 s36, s72, 0x40080
	s_addc_u32 s37, s73, 0
	s_add_i32 s27, s35, s81
	v_lshl_add_u64 v[128:129], s[36:37], 0, v[148:149]
	s_mov_b32 m0, s27
	s_nop 0
	global_load_lds_dwordx4 v[128:129], off
	v_lshl_add_u64 v[128:129], s[36:37], 0, v[146:147]
	s_add_i32 m0, s27, 0x2000
	s_nop 0
	global_load_lds_dwordx4 v[128:129], off
	s_waitcnt vmcnt(6)
	s_barrier
	s_setprio 1
	v_mfma_f32_16x16x32_bf16 v[52:55], v[220:223], v[156:159], v[52:55]
	v_mfma_f32_16x16x32_bf16 v[48:51], v[232:235], v[156:159], v[48:51]
	v_mfma_f32_16x16x32_bf16 v[36:39], v[220:223], v[164:167], v[36:39]
	v_mfma_f32_16x16x32_bf16 v[32:35], v[232:235], v[164:167], v[32:35]
	v_mfma_f32_16x16x32_bf16 v[20:23], v[220:223], v[192:195], v[20:23]
	v_mfma_f32_16x16x32_bf16 v[16:19], v[232:235], v[192:195], v[16:19]
	v_mfma_f32_16x16x32_bf16 v[4:7], v[220:223], v[200:203], v[4:7]
	v_mfma_f32_16x16x32_bf16 v[0:3], v[232:235], v[200:203], v[0:3]
	v_mfma_f32_16x16x32_bf16 v[52:55], v[228:231], v[160:163], v[52:55]
	v_mfma_f32_16x16x32_bf16 v[48:51], v[236:239], v[160:163], v[48:51]
	v_mfma_f32_16x16x32_bf16 v[36:39], v[228:231], v[188:191], v[36:39]
	v_mfma_f32_16x16x32_bf16 v[32:35], v[236:239], v[188:191], v[32:35]
	v_mfma_f32_16x16x32_bf16 v[20:23], v[228:231], v[196:199], v[20:23]
	v_mfma_f32_16x16x32_bf16 v[16:19], v[236:239], v[196:199], v[16:19]
	v_mfma_f32_16x16x32_bf16 v[4:7], v[228:231], v[204:207], v[4:7]
	v_mfma_f32_16x16x32_bf16 v[0:3], v[236:239], v[204:207], v[0:3]
	s_setprio 0
	s_add_i32 s34, s34, 2
	s_add_u32 s52, s52, 0x100
	s_addc_u32 s53, s53, 0
	s_add_u32 s31, s31, 0x100
	s_addc_u32 s33, s33, 0
	s_cmp_gt_u32 s34, 13
	s_barrier
	s_cbranch_scc0 .LBB0_326
	v_lshl_add_u32 v128, s0, 8, v151
	v_readlane_b32 s0, v252, 36
	v_ashrrev_i32_e32 v129, 31, v128
	v_readlane_b32 s1, v252, 37
	v_or_b32_e32 v132, 16, v128
	v_or_b32_e32 v136, 32, v128
	v_lshl_add_u64 v[130:131], v[128:129], 3, s[0:1]
	v_ashrrev_i32_e32 v133, 31, v132
	v_ashrrev_i32_e32 v137, 31, v136
	v_or_b32_e32 v140, 48, v128
	v_lshl_add_u64 v[134:135], v[132:133], 3, s[0:1]
	v_lshl_add_u64 v[138:139], v[136:137], 3, s[0:1]
	v_ashrrev_i32_e32 v141, 31, v140
	global_load_dwordx2 v[202:203], v[130:131], off
	global_load_dwordx2 v[200:201], v[134:135], off
	global_load_dwordx2 v[192:193], v[138:139], off
	global_load_dwordx2 v[166:167], v[130:131], off offset:1024
	v_add_u32_e32 v164, 0x90, v128
	v_add_u32_e32 v158, 0xa0, v128
	v_add_u32_e32 v156, 0xb0, v128
	v_lshl_add_u64 v[142:143], v[140:141], 3, s[0:1]
	v_ashrrev_i32_e32 v165, 31, v164
	v_ashrrev_i32_e32 v159, 31, v158
	v_ashrrev_i32_e32 v157, 31, v156
	v_lshl_add_u64 v[130:131], v[164:165], 3, s[0:1]
	v_lshl_add_u64 v[134:135], v[158:159], 3, s[0:1]
	v_lshl_add_u64 v[138:139], v[156:157], 3, s[0:1]
	global_load_dwordx2 v[196:197], v[142:143], off
	global_load_dwordx2 v[188:189], v[130:131], off
	global_load_dwordx2 v[162:163], v[134:135], off
	global_load_dwordx2 v[160:161], v[138:139], off
	v_add_u32_e32 v168, 0x80, v128
	s_mov_b64 s[0:1], -1
	s_cmp_gt_u32 s10, 1
	v_lshlrev_b32_e32 v144, 1, v150
	v_ashrrev_i32_e32 v169, 31, v168
	v_lshlrev_b64 v[204:205], 10, v[128:129]
	v_lshlrev_b64 v[198:199], 10, v[132:133]
	v_lshlrev_b64 v[194:195], 10, v[136:137]
	v_lshlrev_b64 v[190:191], 10, v[140:141]
	s_waitcnt vmcnt(0)
	v_ffbh_u32_e32 v222, v203
	v_ffbh_u32_e32 v221, v201
	v_ffbh_u32_e32 v220, v193
	v_ffbh_u32_e32 v219, v197
	s_cbranch_scc0 .LBB0_329
	s_cmp_lt_u32 s10, 4
	s_cselect_b64 vcc, -1, 0
	v_readlane_b32 s56, v254, 23
	s_and_b64 s[0:1], vcc, exec
	v_readlane_b32 s70, v254, 37
	v_readlane_b32 s36, v252, 15
	v_readlane_b32 s71, v254, 38
	v_readlane_b32 s37, v252, 16
	s_cselect_b32 s0, s70, s36
	s_mov_b32 s11, 0x4400000
	v_readlane_b32 s30, v254, 62
	s_cselect_b32 s1, s71, s37
	s_cselect_b32 s11, s11, 0x4800000
	v_readlane_b32 s31, v254, 63
	s_add_u32 s0, s0, s30
	s_addc_u32 s1, s1, s31
	global_load_dwordx4 v[136:139], v218, s[0:1] offset:16
	global_load_dwordx4 v[140:143], v218, s[0:1]
	global_load_dwordx4 v[128:131], v218, s[0:1] offset:144
	global_load_dwordx4 v[132:135], v218, s[0:1] offset:128
	v_and_b32_e32 v177, 64, v214
	v_xor_b32_e32 v176, 16, v214
	v_add_u32_e32 v177, 64, v177
	v_cndmask_b32_e32 v223, 1.0, v215, vcc
	v_cmp_lt_i32_e32 vcc, v176, v177
	v_readlane_b32 s9, v254, 52
	s_add_u32 s11, s9, s11
	v_cndmask_b32_e32 v176, v214, v176, vcc
	v_lshlrev_b32_e32 v225, 2, v176
	v_xor_b32_e32 v176, 32, v214
	v_cmp_lt_i32_e32 vcc, v176, v177
	v_readlane_b32 s9, v254, 61
	s_addc_u32 s25, s9, 0
	v_cndmask_b32_e32 v176, v214, v176, vcc
	v_lshlrev_b32_e32 v224, 2, v176
	v_min_u32_e32 v176, 32, v222
	v_lshlrev_b64 v[228:229], v176, v[202:203]
	v_min_u32_e32 v177, 1, v228
	v_or_b32_e32 v177, v229, v177
	v_cvt_f32_u32_e32 v177, v177
	v_sub_u32_e32 v176, 32, v176
	s_lshl_b32 s0, s10, 9
	s_and_b32 s0, s0, 0x200
	v_ldexp_f32 v176, v177, v176
	v_mul_f32_e32 v176, 0x35800000, v176
	v_fmamk_f32 v176, v176, 0x3a800000, v210
	s_add_u32 s0, s11, s0
	v_rsq_f32_e32 v176, v176
	s_addc_u32 s1, s25, 0
	v_lshl_add_u64 v[206:207], s[0:1], 0, v[144:145]
	v_readlane_b32 s48, v252, 27
	v_mov_b32_e32 v228, v176
	v_pk_mul_f32 v[230:231], v[124:125], v[228:229] op_sel_hi:[1,0]
	v_pk_mul_f32 v[232:233], v[126:127], v[228:229] op_sel_hi:[1,0]
	v_pk_mul_f32 v[236:237], v[230:231], v[230:231]
	v_pk_mul_f32 v[234:235], v[232:233], v[232:233]
	v_pk_mul_f32 v[250:251], v[114:115], v[228:229] op_sel_hi:[1,0]
	v_pk_mov_b32 v[238:239], v[236:237], v[234:235] op_sel:[1,0]
	v_mov_b32_e32 v237, v235
	v_pk_add_f32 v[234:235], v[238:239], v[236:237]
	v_pk_mul_f32 v[236:237], v[120:121], v[228:229] op_sel_hi:[1,0]
	v_pk_mul_f32 v[238:239], v[122:123], v[228:229] op_sel_hi:[1,0]
	v_pk_mul_f32 v[242:243], v[236:237], v[236:237]
	v_pk_mul_f32 v[240:241], v[238:239], v[238:239]
	v_pk_add_f32 v[234:235], v[234:235], v[234:235] op_sel_hi:[0,1]
	v_pk_mov_b32 v[244:245], v[242:243], v[240:241] op_sel:[1,0]
	v_mov_b32_e32 v243, v241
	v_pk_add_f32 v[240:241], v[244:245], v[242:243]
	v_pk_mul_f32 v[244:245], v[116:117], v[228:229] op_sel_hi:[1,0]
	v_pk_mul_f32 v[242:243], v[118:119], v[228:229] op_sel_hi:[1,0]
	v_mul_f32_e32 v234, v244, v244
	v_pk_fma_f32 v[246:247], v[244:245], v[244:245], v[234:235] op_sel_hi:[1,1,0]
	v_mul_f32_e32 v234, v242, v242
	v_pk_add_f32 v[240:241], v[240:241], v[240:241] op_sel_hi:[0,1]
	v_pk_fma_f32 v[248:249], v[242:243], v[242:243], v[234:235] op_sel_hi:[1,1,0]
	v_pk_mul_f32 v[176:177], v[112:113], v[228:229] op_sel_hi:[1,0]
	v_mul_f32_e32 v234, v250, v250
	v_mul_f32_e32 v246, v176, v176
	v_mul_f32_e32 v248, v177, v177
	v_mul_f32_e32 v240, v251, v251
	v_pk_add_f32 v[228:229], v[246:247], v[248:249]
	v_pk_add_f32 v[234:235], v[234:235], v[240:241]
	v_lshl_add_u64 v[240:241], v[206:207], 0, v[204:205]
	v_pk_add_f32 v[228:229], v[228:229], v[234:235]
	v_readlane_b32 s57, v254, 24
	v_add_f32_e32 v228, v228, v229
	ds_bpermute_b32 v229, v225, v228
	v_readlane_b32 s58, v254, 25
	v_readlane_b32 s59, v254, 26
	v_readlane_b32 s60, v254, 27
	v_readlane_b32 s61, v254, 28
	s_waitcnt lgkmcnt(0)
	v_add_f32_e32 v228, v228, v229
	ds_bpermute_b32 v229, v224, v228
	v_readlane_b32 s62, v254, 29
	v_readlane_b32 s63, v254, 30
	v_readlane_b32 s64, v254, 31
	v_readlane_b32 s65, v254, 32
	s_waitcnt lgkmcnt(0)
	v_add_f32_e32 v228, v228, v229
	v_fmamk_f32 v228, v228, 0x3c800000, v210
	v_readlane_b32 s66, v254, 33
	v_rsq_f32_e32 v228, v228
	v_readlane_b32 s67, v254, 34
	v_readlane_b32 s68, v254, 35
	v_readlane_b32 s69, v254, 36
	v_mul_f32_e32 v234, v223, v228
	v_pk_mul_f32 v[228:229], v[230:231], v[234:235] op_sel_hi:[1,0]
	v_pk_mul_f32 v[230:231], v[232:233], v[234:235] op_sel_hi:[1,0]
	s_waitcnt vmcnt(2)
	v_pk_mul_f32 v[228:229], v[140:141], v[228:229]
	v_pk_mul_f32 v[230:231], v[142:143], v[230:231]
	v_pk_mul_f32 v[232:233], v[236:237], v[234:235] op_sel_hi:[1,0]
	v_pk_mul_f32 v[236:237], v[238:239], v[234:235] op_sel_hi:[1,0]
	v_cvt_pk_bf16_f32 v228, v228, v229
	v_cvt_pk_bf16_f32 v229, v230, v231
	v_pk_mul_f32 v[232:233], v[136:137], v[232:233]
	v_pk_mul_f32 v[236:237], v[138:139], v[236:237]
	v_cvt_pk_bf16_f32 v230, v232, v233
	v_pk_mul_f32 v[176:177], v[176:177], v[234:235] op_sel_hi:[1,0]
	v_cvt_pk_bf16_f32 v231, v236, v237
	global_store_dwordx4 v[240:241], v[228:231], off
	v_pk_mul_f32 v[232:233], v[250:251], v[234:235] op_sel_hi:[1,0]
	s_waitcnt vmcnt(2)
	v_pk_mul_f32 v[176:177], v[128:129], v[176:177]
	v_pk_mul_f32 v[228:229], v[244:245], v[234:235] op_sel_hi:[1,0]
	v_pk_mul_f32 v[230:231], v[242:243], v[234:235] op_sel_hi:[1,0]
	s_waitcnt vmcnt(1)
	v_pk_mul_f32 v[228:229], v[132:133], v[228:229]
	v_pk_mul_f32 v[230:231], v[134:135], v[230:231]
	v_cvt_pk_bf16_f32 v228, v228, v229
	v_pk_mul_f32 v[232:233], v[130:131], v[232:233]
	v_cvt_pk_bf16_f32 v229, v230, v231
	v_cvt_pk_bf16_f32 v230, v176, v177
	s_nop 1
	v_readlane_b32 s38, v252, 17
	v_cvt_pk_bf16_f32 v231, v232, v233
	s_nop 1
	global_store_dwordx4 v[240:241], v[228:231], off offset:64
	v_readlane_b32 s39, v252, 18
	v_readlane_b32 s40, v252, 19
	v_min_u32_e32 v228, 32, v221
	v_lshlrev_b64 v[176:177], v228, v[200:201]
	v_min_u32_e32 v176, 1, v176
	v_or_b32_e32 v176, v177, v176
	v_cvt_f32_u32_e32 v176, v176
	v_sub_u32_e32 v177, 32, v228
	v_readlane_b32 s41, v252, 20
	v_readlane_b32 s42, v252, 21
	v_ldexp_f32 v176, v176, v177
	v_mul_f32_e32 v176, 0x35800000, v176
	v_fmamk_f32 v176, v176, 0x3a800000, v210
	v_readlane_b32 s43, v252, 22
	v_rsq_f32_e32 v176, v176
	v_readlane_b32 s44, v252, 23
	v_readlane_b32 s45, v252, 24
	v_readlane_b32 s46, v252, 25
	v_pk_mul_f32 v[228:229], v[108:109], v[176:177] op_sel_hi:[1,0]
	v_pk_mul_f32 v[230:231], v[110:111], v[176:177] op_sel_hi:[1,0]
	v_pk_mul_f32 v[234:235], v[228:229], v[228:229]
	v_pk_mul_f32 v[232:233], v[230:231], v[230:231]
	v_pk_mul_f32 v[248:249], v[98:99], v[176:177] op_sel_hi:[1,0]
	v_pk_mov_b32 v[236:237], v[234:235], v[232:233] op_sel:[1,0]
	v_mov_b32_e32 v235, v233
	v_pk_add_f32 v[232:233], v[236:237], v[234:235]
	v_pk_mul_f32 v[234:235], v[104:105], v[176:177] op_sel_hi:[1,0]
	v_pk_mul_f32 v[236:237], v[106:107], v[176:177] op_sel_hi:[1,0]
	v_pk_mul_f32 v[240:241], v[234:235], v[234:235]
	v_pk_mul_f32 v[238:239], v[236:237], v[236:237]
	v_pk_add_f32 v[232:233], v[232:233], v[232:233] op_sel_hi:[0,1]
	v_pk_mov_b32 v[242:243], v[240:241], v[238:239] op_sel:[1,0]
	v_mov_b32_e32 v241, v239
	v_pk_add_f32 v[238:239], v[242:243], v[240:241]
	v_pk_mul_f32 v[242:243], v[100:101], v[176:177] op_sel_hi:[1,0]
	v_pk_mul_f32 v[240:241], v[102:103], v[176:177] op_sel_hi:[1,0]
	v_mul_f32_e32 v232, v242, v242
	v_pk_fma_f32 v[244:245], v[242:243], v[242:243], v[232:233] op_sel_hi:[1,1,0]
	v_mul_f32_e32 v232, v240, v240
	v_pk_add_f32 v[238:239], v[238:239], v[238:239] op_sel_hi:[0,1]
	v_pk_fma_f32 v[246:247], v[240:241], v[240:241], v[232:233] op_sel_hi:[1,1,0]
	v_pk_mul_f32 v[176:177], v[96:97], v[176:177] op_sel_hi:[1,0]
	v_mul_f32_e32 v232, v248, v248
	v_mul_f32_e32 v244, v176, v176
	v_mul_f32_e32 v246, v177, v177
	v_mul_f32_e32 v238, v249, v249
	v_pk_add_f32 v[244:245], v[244:245], v[246:247]
	v_pk_add_f32 v[232:233], v[232:233], v[238:239]
	v_lshl_add_u64 v[238:239], v[206:207], 0, v[198:199]
	v_pk_add_f32 v[232:233], v[244:245], v[232:233]
	v_readlane_b32 s47, v252, 26
	v_add_f32_e32 v232, v232, v233
	ds_bpermute_b32 v233, v225, v232
	v_readlane_b32 s49, v252, 28
	v_readlane_b32 s50, v252, 29
	v_readlane_b32 s51, v252, 30
	v_readlane_b32 s48, v252, 40
	s_waitcnt lgkmcnt(0)
	v_add_f32_e32 v232, v232, v233
	ds_bpermute_b32 v233, v224, v232
	s_mov_b64 s[0:1], 0
	s_waitcnt lgkmcnt(0)
	v_add_f32_e32 v232, v232, v233
	v_fmamk_f32 v232, v232, 0x3c800000, v210
	s_nop 0
	v_rsq_f32_e32 v232, v232
	s_nop 0
	v_mul_f32_e32 v232, v223, v232
	v_pk_mul_f32 v[228:229], v[228:229], v[232:233] op_sel_hi:[1,0]
	v_pk_mul_f32 v[230:231], v[230:231], v[232:233] op_sel_hi:[1,0]
	v_pk_mul_f32 v[228:229], v[140:141], v[228:229]
	v_pk_mul_f32 v[230:231], v[142:143], v[230:231]
	v_pk_mul_f32 v[234:235], v[234:235], v[232:233] op_sel_hi:[1,0]
	v_pk_mul_f32 v[236:237], v[236:237], v[232:233] op_sel_hi:[1,0]
	v_cvt_pk_bf16_f32 v228, v228, v229
	v_cvt_pk_bf16_f32 v229, v230, v231
	v_pk_mul_f32 v[234:235], v[136:137], v[234:235]
	v_pk_mul_f32 v[236:237], v[138:139], v[236:237]
	v_cvt_pk_bf16_f32 v230, v234, v235
	v_pk_mul_f32 v[176:177], v[176:177], v[232:233] op_sel_hi:[1,0]
	v_cvt_pk_bf16_f32 v231, v236, v237
	global_store_dwordx4 v[238:239], v[228:231], off
	v_pk_mul_f32 v[176:177], v[128:129], v[176:177]
	s_nop 0
	v_pk_mul_f32 v[228:229], v[242:243], v[232:233] op_sel_hi:[1,0]
	v_pk_mul_f32 v[230:231], v[240:241], v[232:233] op_sel_hi:[1,0]
	v_pk_mul_f32 v[228:229], v[132:133], v[228:229]
	v_pk_mul_f32 v[230:231], v[134:135], v[230:231]
	v_pk_mul_f32 v[232:233], v[248:249], v[232:233] op_sel_hi:[1,0]
	v_cvt_pk_bf16_f32 v228, v228, v229
	v_cvt_pk_bf16_f32 v229, v230, v231
	v_cvt_pk_bf16_f32 v230, v176, v177
	s_nop 0
	v_pk_mul_f32 v[232:233], v[130:131], v[232:233]
	s_nop 0
	v_cvt_pk_bf16_f32 v231, v232, v233
	global_store_dwordx4 v[238:239], v[228:231], off offset:64
	s_nop 1
	v_min_u32_e32 v228, 32, v220
	v_lshlrev_b64 v[176:177], v228, v[192:193]
	v_min_u32_e32 v176, 1, v176
	v_or_b32_e32 v176, v177, v176
	v_cvt_f32_u32_e32 v176, v176
	v_sub_u32_e32 v177, 32, v228
	v_ldexp_f32 v176, v176, v177
	v_mul_f32_e32 v176, 0x35800000, v176
	v_fmamk_f32 v176, v176, 0x3a800000, v210
	s_nop 0
	v_rsq_f32_e32 v176, v176
	s_nop 0
	v_pk_mul_f32 v[228:229], v[92:93], v[176:177] op_sel_hi:[1,0]
	v_pk_mul_f32 v[230:231], v[94:95], v[176:177] op_sel_hi:[1,0]
	v_pk_mul_f32 v[234:235], v[228:229], v[228:229]
	v_pk_mul_f32 v[232:233], v[230:231], v[230:231]
	v_pk_mul_f32 v[248:249], v[82:83], v[176:177] op_sel_hi:[1,0]
	v_pk_mov_b32 v[236:237], v[234:235], v[232:233] op_sel:[1,0]
	v_mov_b32_e32 v235, v233
	v_pk_add_f32 v[232:233], v[236:237], v[234:235]
	v_pk_mul_f32 v[234:235], v[88:89], v[176:177] op_sel_hi:[1,0]
	v_pk_mul_f32 v[236:237], v[90:91], v[176:177] op_sel_hi:[1,0]
	v_pk_mul_f32 v[240:241], v[234:235], v[234:235]
	v_pk_mul_f32 v[238:239], v[236:237], v[236:237]
	v_pk_add_f32 v[232:233], v[232:233], v[232:233] op_sel_hi:[0,1]
	v_pk_mov_b32 v[242:243], v[240:241], v[238:239] op_sel:[1,0]
	v_mov_b32_e32 v241, v239
	v_pk_add_f32 v[238:239], v[242:243], v[240:241]
	v_pk_mul_f32 v[242:243], v[84:85], v[176:177] op_sel_hi:[1,0]
	v_pk_mul_f32 v[240:241], v[86:87], v[176:177] op_sel_hi:[1,0]
	v_mul_f32_e32 v232, v242, v242
	v_pk_fma_f32 v[244:245], v[242:243], v[242:243], v[232:233] op_sel_hi:[1,1,0]
	v_mul_f32_e32 v232, v240, v240
	v_pk_add_f32 v[238:239], v[238:239], v[238:239] op_sel_hi:[0,1]
	v_pk_fma_f32 v[246:247], v[240:241], v[240:241], v[232:233] op_sel_hi:[1,1,0]
	v_pk_mul_f32 v[176:177], v[80:81], v[176:177] op_sel_hi:[1,0]
	v_mul_f32_e32 v232, v248, v248
	v_mul_f32_e32 v244, v176, v176
	v_mul_f32_e32 v246, v177, v177
	v_mul_f32_e32 v238, v249, v249
	v_pk_add_f32 v[244:245], v[244:245], v[246:247]
	v_pk_add_f32 v[232:233], v[232:233], v[238:239]
	v_lshl_add_u64 v[238:239], v[206:207], 0, v[194:195]
	v_pk_add_f32 v[232:233], v[244:245], v[232:233]
	s_nop 0
	v_add_f32_e32 v232, v232, v233
	ds_bpermute_b32 v233, v225, v232
	s_waitcnt lgkmcnt(0)
	v_add_f32_e32 v232, v232, v233
	ds_bpermute_b32 v233, v224, v232
	s_waitcnt lgkmcnt(0)
	v_add_f32_e32 v232, v232, v233
	v_fmamk_f32 v232, v232, 0x3c800000, v210
	s_nop 0
	v_rsq_f32_e32 v232, v232
	s_nop 0
	v_mul_f32_e32 v232, v223, v232
	v_pk_mul_f32 v[228:229], v[228:229], v[232:233] op_sel_hi:[1,0]
	v_pk_mul_f32 v[230:231], v[230:231], v[232:233] op_sel_hi:[1,0]
	v_pk_mul_f32 v[228:229], v[140:141], v[228:229]
	v_pk_mul_f32 v[230:231], v[142:143], v[230:231]
	v_pk_mul_f32 v[234:235], v[234:235], v[232:233] op_sel_hi:[1,0]
	v_pk_mul_f32 v[236:237], v[236:237], v[232:233] op_sel_hi:[1,0]
	v_cvt_pk_bf16_f32 v228, v228, v229
	v_cvt_pk_bf16_f32 v229, v230, v231
	v_pk_mul_f32 v[234:235], v[136:137], v[234:235]
	v_pk_mul_f32 v[236:237], v[138:139], v[236:237]
	v_cvt_pk_bf16_f32 v230, v234, v235
	v_pk_mul_f32 v[176:177], v[176:177], v[232:233] op_sel_hi:[1,0]
	v_cvt_pk_bf16_f32 v231, v236, v237
	global_store_dwordx4 v[238:239], v[228:231], off
	v_pk_mul_f32 v[176:177], v[128:129], v[176:177]
	s_nop 0
	v_pk_mul_f32 v[228:229], v[242:243], v[232:233] op_sel_hi:[1,0]
	v_pk_mul_f32 v[230:231], v[240:241], v[232:233] op_sel_hi:[1,0]
	v_pk_mul_f32 v[228:229], v[132:133], v[228:229]
	v_pk_mul_f32 v[230:231], v[134:135], v[230:231]
	v_pk_mul_f32 v[232:233], v[248:249], v[232:233] op_sel_hi:[1,0]
	v_cvt_pk_bf16_f32 v228, v228, v229
	v_cvt_pk_bf16_f32 v229, v230, v231
	v_cvt_pk_bf16_f32 v230, v176, v177
	s_nop 0
	v_pk_mul_f32 v[232:233], v[130:131], v[232:233]
	s_nop 0
	v_cvt_pk_bf16_f32 v231, v232, v233
	global_store_dwordx4 v[238:239], v[228:231], off offset:64
	s_nop 1
	v_min_u32_e32 v228, 32, v219
	v_lshlrev_b64 v[176:177], v228, v[196:197]
	v_min_u32_e32 v176, 1, v176
	v_or_b32_e32 v176, v177, v176
	v_cvt_f32_u32_e32 v176, v176
	v_sub_u32_e32 v177, 32, v228
	v_ldexp_f32 v176, v176, v177
	v_mul_f32_e32 v176, 0x35800000, v176
	v_fmamk_f32 v176, v176, 0x3a800000, v210
	s_nop 0
	v_rsq_f32_e32 v176, v176
	s_nop 0
	v_pk_mul_f32 v[228:229], v[76:77], v[176:177] op_sel_hi:[1,0]
	v_pk_mul_f32 v[230:231], v[78:79], v[176:177] op_sel_hi:[1,0]
	v_pk_mul_f32 v[234:235], v[228:229], v[228:229]
	v_pk_mul_f32 v[232:233], v[230:231], v[230:231]
	v_pk_mul_f32 v[248:249], v[66:67], v[176:177] op_sel_hi:[1,0]
	v_pk_mov_b32 v[236:237], v[234:235], v[232:233] op_sel:[1,0]
	v_mov_b32_e32 v235, v233
	v_pk_add_f32 v[232:233], v[236:237], v[234:235]
	v_pk_mul_f32 v[234:235], v[72:73], v[176:177] op_sel_hi:[1,0]
	v_pk_mul_f32 v[236:237], v[74:75], v[176:177] op_sel_hi:[1,0]
	v_pk_mul_f32 v[240:241], v[234:235], v[234:235]
	v_pk_mul_f32 v[238:239], v[236:237], v[236:237]
	v_pk_add_f32 v[232:233], v[232:233], v[232:233] op_sel_hi:[0,1]
	v_pk_mov_b32 v[242:243], v[240:241], v[238:239] op_sel:[1,0]
	v_mov_b32_e32 v241, v239
	v_pk_add_f32 v[238:239], v[242:243], v[240:241]
	v_pk_mul_f32 v[242:243], v[68:69], v[176:177] op_sel_hi:[1,0]
	v_pk_mul_f32 v[240:241], v[70:71], v[176:177] op_sel_hi:[1,0]
	v_mul_f32_e32 v232, v242, v242
	v_pk_fma_f32 v[244:245], v[242:243], v[242:243], v[232:233] op_sel_hi:[1,1,0]
	v_mul_f32_e32 v232, v240, v240
	v_pk_add_f32 v[238:239], v[238:239], v[238:239] op_sel_hi:[0,1]
	v_pk_fma_f32 v[246:247], v[240:241], v[240:241], v[232:233] op_sel_hi:[1,1,0]
	v_pk_mul_f32 v[176:177], v[64:65], v[176:177] op_sel_hi:[1,0]
	v_mul_f32_e32 v232, v248, v248
	v_mul_f32_e32 v244, v176, v176
	v_mul_f32_e32 v246, v177, v177
	v_mul_f32_e32 v238, v249, v249
	v_pk_add_f32 v[244:245], v[244:245], v[246:247]
	v_pk_add_f32 v[232:233], v[232:233], v[238:239]
	v_lshl_add_u64 v[238:239], v[206:207], 0, v[190:191]
	v_pk_add_f32 v[232:233], v[244:245], v[232:233]
	s_nop 0
	v_add_f32_e32 v232, v232, v233
	ds_bpermute_b32 v233, v225, v232
	s_waitcnt lgkmcnt(0)
	v_add_f32_e32 v232, v232, v233
	ds_bpermute_b32 v233, v224, v232
	s_waitcnt lgkmcnt(0)
	v_add_f32_e32 v232, v232, v233
	v_fmamk_f32 v232, v232, 0x3c800000, v210
	s_nop 0
	v_rsq_f32_e32 v232, v232
	s_nop 0
	v_mul_f32_e32 v232, v223, v232
	v_pk_mul_f32 v[228:229], v[228:229], v[232:233] op_sel_hi:[1,0]
	v_pk_mul_f32 v[230:231], v[230:231], v[232:233] op_sel_hi:[1,0]
	v_pk_mul_f32 v[228:229], v[140:141], v[228:229]
	v_pk_mul_f32 v[230:231], v[142:143], v[230:231]
	v_pk_mul_f32 v[234:235], v[234:235], v[232:233] op_sel_hi:[1,0]
	v_pk_mul_f32 v[236:237], v[236:237], v[232:233] op_sel_hi:[1,0]
	v_pk_mul_f32 v[234:235], v[136:137], v[234:235]
	v_pk_mul_f32 v[236:237], v[138:139], v[236:237]
	v_cvt_pk_bf16_f32 v228, v228, v229
	v_cvt_pk_bf16_f32 v229, v230, v231
	v_cvt_pk_bf16_f32 v230, v234, v235
	v_pk_mul_f32 v[176:177], v[176:177], v[232:233] op_sel_hi:[1,0]
	v_cvt_pk_bf16_f32 v231, v236, v237
	global_store_dwordx4 v[238:239], v[228:231], off
	v_pk_mul_f32 v[176:177], v[128:129], v[176:177]
	s_nop 0
	v_pk_mul_f32 v[228:229], v[242:243], v[232:233] op_sel_hi:[1,0]
	v_pk_mul_f32 v[230:231], v[240:241], v[232:233] op_sel_hi:[1,0]
	v_pk_mul_f32 v[228:229], v[132:133], v[228:229]
	v_pk_mul_f32 v[230:231], v[134:135], v[230:231]
	v_pk_mul_f32 v[232:233], v[248:249], v[232:233] op_sel_hi:[1,0]
	v_cvt_pk_bf16_f32 v228, v228, v229
	v_cvt_pk_bf16_f32 v229, v230, v231
	v_cvt_pk_bf16_f32 v230, v176, v177
	v_ffbh_u32_e32 v176, v167
	v_pk_mul_f32 v[232:233], v[130:131], v[232:233]
	s_nop 0
	v_cvt_pk_bf16_f32 v231, v232, v233
	global_store_dwordx4 v[238:239], v[228:231], off offset:64
	s_nop 1
	v_min_u32_e32 v228, 32, v176
	v_lshlrev_b64 v[176:177], v228, v[166:167]
	v_min_u32_e32 v176, 1, v176
	v_or_b32_e32 v176, v177, v176
	v_cvt_f32_u32_e32 v176, v176
	v_sub_u32_e32 v177, 32, v228
	v_ldexp_f32 v176, v176, v177
	v_mul_f32_e32 v176, 0x35800000, v176
	v_fmamk_f32 v176, v176, 0x3a800000, v210
	s_nop 0
	v_rsq_f32_e32 v176, v176
	s_nop 0
	v_pk_mul_f32 v[228:229], v[60:61], v[176:177] op_sel_hi:[1,0]
	v_pk_mul_f32 v[230:231], v[62:63], v[176:177] op_sel_hi:[1,0]
	v_pk_mul_f32 v[234:235], v[228:229], v[228:229]
	v_pk_mul_f32 v[232:233], v[230:231], v[230:231]
	v_pk_mul_f32 v[248:249], v[50:51], v[176:177] op_sel_hi:[1,0]
	v_pk_mov_b32 v[236:237], v[234:235], v[232:233] op_sel:[1,0]
	v_mov_b32_e32 v235, v233
	v_pk_add_f32 v[232:233], v[236:237], v[234:235]
	v_pk_mul_f32 v[234:235], v[56:57], v[176:177] op_sel_hi:[1,0]
	v_pk_mul_f32 v[236:237], v[58:59], v[176:177] op_sel_hi:[1,0]
	v_pk_mul_f32 v[240:241], v[234:235], v[234:235]
	v_pk_mul_f32 v[238:239], v[236:237], v[236:237]
	v_pk_add_f32 v[232:233], v[232:233], v[232:233] op_sel_hi:[0,1]
	v_pk_mov_b32 v[242:243], v[240:241], v[238:239] op_sel:[1,0]
	v_mov_b32_e32 v241, v239
	v_pk_add_f32 v[238:239], v[242:243], v[240:241]
	v_pk_mul_f32 v[242:243], v[52:53], v[176:177] op_sel_hi:[1,0]
	v_pk_mul_f32 v[240:241], v[54:55], v[176:177] op_sel_hi:[1,0]
	v_mul_f32_e32 v232, v242, v242
	v_pk_fma_f32 v[244:245], v[242:243], v[242:243], v[232:233] op_sel_hi:[1,1,0]
	v_mul_f32_e32 v232, v240, v240
	v_pk_add_f32 v[238:239], v[238:239], v[238:239] op_sel_hi:[0,1]
	v_pk_fma_f32 v[246:247], v[240:241], v[240:241], v[232:233] op_sel_hi:[1,1,0]
	v_pk_mul_f32 v[176:177], v[48:49], v[176:177] op_sel_hi:[1,0]
	v_mul_f32_e32 v232, v248, v248
	v_mul_f32_e32 v244, v176, v176
	v_mul_f32_e32 v246, v177, v177
	v_mul_f32_e32 v238, v249, v249
	v_pk_add_f32 v[244:245], v[244:245], v[246:247]
	v_pk_add_f32 v[232:233], v[232:233], v[238:239]
	v_lshlrev_b64 v[238:239], 10, v[168:169]
	v_pk_add_f32 v[232:233], v[244:245], v[232:233]
	v_lshl_add_u64 v[238:239], v[206:207], 0, v[238:239]
	v_add_f32_e32 v232, v232, v233
	ds_bpermute_b32 v233, v225, v232
	s_waitcnt lgkmcnt(0)
	v_add_f32_e32 v232, v232, v233
	ds_bpermute_b32 v233, v224, v232
	s_waitcnt lgkmcnt(0)
	v_add_f32_e32 v232, v232, v233
	v_fmamk_f32 v232, v232, 0x3c800000, v210
	s_nop 0
	v_rsq_f32_e32 v232, v232
	s_nop 0
	v_mul_f32_e32 v232, v223, v232
	v_pk_mul_f32 v[228:229], v[228:229], v[232:233] op_sel_hi:[1,0]
	v_pk_mul_f32 v[230:231], v[230:231], v[232:233] op_sel_hi:[1,0]
	v_pk_mul_f32 v[228:229], v[140:141], v[228:229]
	v_pk_mul_f32 v[230:231], v[142:143], v[230:231]
	v_pk_mul_f32 v[234:235], v[234:235], v[232:233] op_sel_hi:[1,0]
	v_pk_mul_f32 v[236:237], v[236:237], v[232:233] op_sel_hi:[1,0]
	v_pk_mul_f32 v[234:235], v[136:137], v[234:235]
	v_pk_mul_f32 v[236:237], v[138:139], v[236:237]
	v_cvt_pk_bf16_f32 v228, v228, v229
	v_cvt_pk_bf16_f32 v229, v230, v231
	v_cvt_pk_bf16_f32 v230, v234, v235
	v_pk_mul_f32 v[176:177], v[176:177], v[232:233] op_sel_hi:[1,0]
	v_cvt_pk_bf16_f32 v231, v236, v237
	global_store_dwordx4 v[238:239], v[228:231], off
	v_pk_mul_f32 v[176:177], v[128:129], v[176:177]
	s_nop 0
	v_pk_mul_f32 v[228:229], v[242:243], v[232:233] op_sel_hi:[1,0]
	v_pk_mul_f32 v[230:231], v[240:241], v[232:233] op_sel_hi:[1,0]
	v_pk_mul_f32 v[228:229], v[132:133], v[228:229]
	v_pk_mul_f32 v[230:231], v[134:135], v[230:231]
	v_pk_mul_f32 v[232:233], v[248:249], v[232:233] op_sel_hi:[1,0]
	v_cvt_pk_bf16_f32 v228, v228, v229
	v_cvt_pk_bf16_f32 v229, v230, v231
	v_cvt_pk_bf16_f32 v230, v176, v177
	v_ffbh_u32_e32 v176, v189
	v_pk_mul_f32 v[232:233], v[130:131], v[232:233]
	s_nop 0
	v_cvt_pk_bf16_f32 v231, v232, v233
	global_store_dwordx4 v[238:239], v[228:231], off offset:64
	s_nop 1
	v_min_u32_e32 v228, 32, v176
	v_lshlrev_b64 v[176:177], v228, v[188:189]
	v_min_u32_e32 v176, 1, v176
	v_or_b32_e32 v176, v177, v176
	v_cvt_f32_u32_e32 v176, v176
	v_sub_u32_e32 v177, 32, v228
	v_ldexp_f32 v176, v176, v177
	v_mul_f32_e32 v176, 0x35800000, v176
	v_fmamk_f32 v176, v176, 0x3a800000, v210
	s_nop 0
	v_rsq_f32_e32 v176, v176
	s_nop 0
	v_pk_mul_f32 v[228:229], v[44:45], v[176:177] op_sel_hi:[1,0]
	v_pk_mul_f32 v[230:231], v[46:47], v[176:177] op_sel_hi:[1,0]
	v_pk_mul_f32 v[234:235], v[228:229], v[228:229]
	v_pk_mul_f32 v[232:233], v[230:231], v[230:231]
	v_pk_mul_f32 v[248:249], v[34:35], v[176:177] op_sel_hi:[1,0]
	v_pk_mov_b32 v[236:237], v[234:235], v[232:233] op_sel:[1,0]
	v_mov_b32_e32 v235, v233
	v_pk_add_f32 v[232:233], v[236:237], v[234:235]
	v_pk_mul_f32 v[234:235], v[40:41], v[176:177] op_sel_hi:[1,0]
	v_pk_mul_f32 v[236:237], v[42:43], v[176:177] op_sel_hi:[1,0]
	v_pk_mul_f32 v[240:241], v[234:235], v[234:235]
	v_pk_mul_f32 v[238:239], v[236:237], v[236:237]
	v_pk_add_f32 v[232:233], v[232:233], v[232:233] op_sel_hi:[0,1]
	v_pk_mov_b32 v[242:243], v[240:241], v[238:239] op_sel:[1,0]
	v_mov_b32_e32 v241, v239
	v_pk_add_f32 v[238:239], v[242:243], v[240:241]
	v_pk_mul_f32 v[242:243], v[36:37], v[176:177] op_sel_hi:[1,0]
	v_pk_mul_f32 v[240:241], v[38:39], v[176:177] op_sel_hi:[1,0]
	v_mul_f32_e32 v232, v242, v242
	v_pk_fma_f32 v[244:245], v[242:243], v[242:243], v[232:233] op_sel_hi:[1,1,0]
	v_mul_f32_e32 v232, v240, v240
	v_pk_add_f32 v[238:239], v[238:239], v[238:239] op_sel_hi:[0,1]
	v_pk_fma_f32 v[246:247], v[240:241], v[240:241], v[232:233] op_sel_hi:[1,1,0]
	v_pk_mul_f32 v[176:177], v[32:33], v[176:177] op_sel_hi:[1,0]
	v_mul_f32_e32 v232, v248, v248
	v_mul_f32_e32 v244, v176, v176
	v_mul_f32_e32 v246, v177, v177
	v_mul_f32_e32 v238, v249, v249
	v_pk_add_f32 v[244:245], v[244:245], v[246:247]
	v_pk_add_f32 v[232:233], v[232:233], v[238:239]
	v_lshlrev_b64 v[238:239], 10, v[164:165]
	v_pk_add_f32 v[232:233], v[244:245], v[232:233]
	v_lshl_add_u64 v[238:239], v[206:207], 0, v[238:239]
	v_add_f32_e32 v232, v232, v233
	ds_bpermute_b32 v233, v225, v232
	s_waitcnt lgkmcnt(0)
	v_add_f32_e32 v232, v232, v233
	ds_bpermute_b32 v233, v224, v232
	s_waitcnt lgkmcnt(0)
	v_add_f32_e32 v232, v232, v233
	v_fmamk_f32 v232, v232, 0x3c800000, v210
	s_nop 0
	v_rsq_f32_e32 v232, v232
	s_nop 0
	v_mul_f32_e32 v232, v223, v232
	v_pk_mul_f32 v[228:229], v[228:229], v[232:233] op_sel_hi:[1,0]
	v_pk_mul_f32 v[230:231], v[230:231], v[232:233] op_sel_hi:[1,0]
	v_pk_mul_f32 v[228:229], v[140:141], v[228:229]
	v_pk_mul_f32 v[230:231], v[142:143], v[230:231]
	v_pk_mul_f32 v[234:235], v[234:235], v[232:233] op_sel_hi:[1,0]
	v_pk_mul_f32 v[236:237], v[236:237], v[232:233] op_sel_hi:[1,0]
	v_pk_mul_f32 v[234:235], v[136:137], v[234:235]
	v_pk_mul_f32 v[236:237], v[138:139], v[236:237]
	v_cvt_pk_bf16_f32 v228, v228, v229
	v_cvt_pk_bf16_f32 v229, v230, v231
	v_cvt_pk_bf16_f32 v230, v234, v235
	v_pk_mul_f32 v[176:177], v[176:177], v[232:233] op_sel_hi:[1,0]
	v_cvt_pk_bf16_f32 v231, v236, v237
	global_store_dwordx4 v[238:239], v[228:231], off
	v_pk_mul_f32 v[176:177], v[128:129], v[176:177]
	s_nop 0
	v_pk_mul_f32 v[228:229], v[242:243], v[232:233] op_sel_hi:[1,0]
	v_pk_mul_f32 v[230:231], v[240:241], v[232:233] op_sel_hi:[1,0]
	v_pk_mul_f32 v[228:229], v[132:133], v[228:229]
	v_pk_mul_f32 v[230:231], v[134:135], v[230:231]
	v_pk_mul_f32 v[232:233], v[248:249], v[232:233] op_sel_hi:[1,0]
	v_cvt_pk_bf16_f32 v228, v228, v229
	v_cvt_pk_bf16_f32 v229, v230, v231
	v_cvt_pk_bf16_f32 v230, v176, v177
	v_ffbh_u32_e32 v176, v163
	v_pk_mul_f32 v[232:233], v[130:131], v[232:233]
	s_nop 0
	v_cvt_pk_bf16_f32 v231, v232, v233
	global_store_dwordx4 v[238:239], v[228:231], off offset:64
	s_nop 1
	v_min_u32_e32 v228, 32, v176
	v_lshlrev_b64 v[176:177], v228, v[162:163]
	v_min_u32_e32 v176, 1, v176
	v_or_b32_e32 v176, v177, v176
	v_cvt_f32_u32_e32 v176, v176
	v_sub_u32_e32 v177, 32, v228
	v_ldexp_f32 v176, v176, v177
	v_mul_f32_e32 v176, 0x35800000, v176
	v_fmamk_f32 v176, v176, 0x3a800000, v210
	s_nop 0
	v_rsq_f32_e32 v176, v176
	s_nop 0
	v_pk_mul_f32 v[228:229], v[28:29], v[176:177] op_sel_hi:[1,0]
	v_pk_mul_f32 v[230:231], v[30:31], v[176:177] op_sel_hi:[1,0]
	v_pk_mul_f32 v[234:235], v[228:229], v[228:229]
	v_pk_mul_f32 v[232:233], v[230:231], v[230:231]
	v_pk_mul_f32 v[248:249], v[18:19], v[176:177] op_sel_hi:[1,0]
	v_pk_mov_b32 v[236:237], v[234:235], v[232:233] op_sel:[1,0]
	v_mov_b32_e32 v235, v233
	v_pk_add_f32 v[232:233], v[236:237], v[234:235]
	v_pk_mul_f32 v[234:235], v[24:25], v[176:177] op_sel_hi:[1,0]
	v_pk_mul_f32 v[236:237], v[26:27], v[176:177] op_sel_hi:[1,0]
	v_pk_mul_f32 v[240:241], v[234:235], v[234:235]
	v_pk_mul_f32 v[238:239], v[236:237], v[236:237]
	v_pk_add_f32 v[232:233], v[232:233], v[232:233] op_sel_hi:[0,1]
	v_pk_mov_b32 v[242:243], v[240:241], v[238:239] op_sel:[1,0]
	v_mov_b32_e32 v241, v239
	v_pk_add_f32 v[238:239], v[242:243], v[240:241]
	v_pk_mul_f32 v[242:243], v[20:21], v[176:177] op_sel_hi:[1,0]
	v_pk_mul_f32 v[240:241], v[22:23], v[176:177] op_sel_hi:[1,0]
	v_mul_f32_e32 v232, v242, v242
	v_pk_fma_f32 v[244:245], v[242:243], v[242:243], v[232:233] op_sel_hi:[1,1,0]
	v_mul_f32_e32 v232, v240, v240
	v_pk_add_f32 v[238:239], v[238:239], v[238:239] op_sel_hi:[0,1]
	v_pk_fma_f32 v[246:247], v[240:241], v[240:241], v[232:233] op_sel_hi:[1,1,0]
	v_pk_mul_f32 v[176:177], v[16:17], v[176:177] op_sel_hi:[1,0]
	v_mul_f32_e32 v232, v248, v248
	v_mul_f32_e32 v244, v176, v176
	v_mul_f32_e32 v246, v177, v177
	v_mul_f32_e32 v238, v249, v249
	v_pk_add_f32 v[244:245], v[244:245], v[246:247]
	v_pk_add_f32 v[232:233], v[232:233], v[238:239]
	v_lshlrev_b64 v[238:239], 10, v[158:159]
	v_pk_add_f32 v[232:233], v[244:245], v[232:233]
	v_lshl_add_u64 v[238:239], v[206:207], 0, v[238:239]
	v_add_f32_e32 v232, v232, v233
	ds_bpermute_b32 v233, v225, v232
	s_waitcnt lgkmcnt(0)
	v_add_f32_e32 v232, v232, v233
	ds_bpermute_b32 v233, v224, v232
	s_waitcnt lgkmcnt(0)
	v_add_f32_e32 v232, v232, v233
	v_fmamk_f32 v232, v232, 0x3c800000, v210
	s_nop 0
	v_rsq_f32_e32 v232, v232
	s_nop 0
	v_mul_f32_e32 v232, v223, v232
	v_pk_mul_f32 v[228:229], v[228:229], v[232:233] op_sel_hi:[1,0]
	v_pk_mul_f32 v[230:231], v[230:231], v[232:233] op_sel_hi:[1,0]
	v_pk_mul_f32 v[228:229], v[140:141], v[228:229]
	v_pk_mul_f32 v[230:231], v[142:143], v[230:231]
	v_pk_mul_f32 v[234:235], v[234:235], v[232:233] op_sel_hi:[1,0]
	v_pk_mul_f32 v[236:237], v[236:237], v[232:233] op_sel_hi:[1,0]
	v_pk_mul_f32 v[234:235], v[136:137], v[234:235]
	v_pk_mul_f32 v[236:237], v[138:139], v[236:237]
	v_cvt_pk_bf16_f32 v228, v228, v229
	v_cvt_pk_bf16_f32 v229, v230, v231
	v_cvt_pk_bf16_f32 v230, v234, v235
	v_pk_mul_f32 v[176:177], v[176:177], v[232:233] op_sel_hi:[1,0]
	v_cvt_pk_bf16_f32 v231, v236, v237
	global_store_dwordx4 v[238:239], v[228:231], off
	v_pk_mul_f32 v[176:177], v[128:129], v[176:177]
	s_nop 0
	v_pk_mul_f32 v[228:229], v[242:243], v[232:233] op_sel_hi:[1,0]
	v_pk_mul_f32 v[230:231], v[240:241], v[232:233] op_sel_hi:[1,0]
	v_pk_mul_f32 v[228:229], v[132:133], v[228:229]
	v_pk_mul_f32 v[230:231], v[134:135], v[230:231]
	v_pk_mul_f32 v[232:233], v[248:249], v[232:233] op_sel_hi:[1,0]
	v_cvt_pk_bf16_f32 v228, v228, v229
	v_cvt_pk_bf16_f32 v229, v230, v231
	v_cvt_pk_bf16_f32 v230, v176, v177
	v_ffbh_u32_e32 v176, v161
	v_pk_mul_f32 v[232:233], v[130:131], v[232:233]
	s_nop 0
	v_cvt_pk_bf16_f32 v231, v232, v233
	global_store_dwordx4 v[238:239], v[228:231], off offset:64
	s_nop 1
	v_min_u32_e32 v228, 32, v176
	v_lshlrev_b64 v[176:177], v228, v[160:161]
	v_min_u32_e32 v176, 1, v176
	v_or_b32_e32 v176, v177, v176
	v_cvt_f32_u32_e32 v176, v176
	v_sub_u32_e32 v177, 32, v228
	v_ldexp_f32 v176, v176, v177
	v_mul_f32_e32 v176, 0x35800000, v176
	v_fmamk_f32 v176, v176, 0x3a800000, v210
	s_nop 0
	v_rsq_f32_e32 v176, v176
	s_nop 0
	v_pk_mul_f32 v[228:229], v[12:13], v[176:177] op_sel_hi:[1,0]
	v_pk_mul_f32 v[230:231], v[14:15], v[176:177] op_sel_hi:[1,0]
	v_pk_mul_f32 v[234:235], v[228:229], v[228:229]
	v_pk_mul_f32 v[232:233], v[230:231], v[230:231]
	v_pk_mul_f32 v[248:249], v[2:3], v[176:177] op_sel_hi:[1,0]
	v_pk_mov_b32 v[236:237], v[234:235], v[232:233] op_sel:[1,0]
	v_mov_b32_e32 v235, v233
	v_pk_add_f32 v[232:233], v[236:237], v[234:235]
	v_pk_mul_f32 v[234:235], v[8:9], v[176:177] op_sel_hi:[1,0]
	v_pk_mul_f32 v[236:237], v[10:11], v[176:177] op_sel_hi:[1,0]
	v_pk_mul_f32 v[240:241], v[234:235], v[234:235]
	v_pk_mul_f32 v[238:239], v[236:237], v[236:237]
	v_pk_add_f32 v[232:233], v[232:233], v[232:233] op_sel_hi:[0,1]
	v_pk_mov_b32 v[242:243], v[240:241], v[238:239] op_sel:[1,0]
	v_mov_b32_e32 v241, v239
	v_pk_add_f32 v[238:239], v[242:243], v[240:241]
	v_pk_mul_f32 v[242:243], v[4:5], v[176:177] op_sel_hi:[1,0]
	v_pk_mul_f32 v[240:241], v[6:7], v[176:177] op_sel_hi:[1,0]
	v_mul_f32_e32 v232, v242, v242
	v_pk_fma_f32 v[244:245], v[242:243], v[242:243], v[232:233] op_sel_hi:[1,1,0]
	v_mul_f32_e32 v232, v240, v240
	v_pk_add_f32 v[238:239], v[238:239], v[238:239] op_sel_hi:[0,1]
	v_pk_fma_f32 v[246:247], v[240:241], v[240:241], v[232:233] op_sel_hi:[1,1,0]
	v_pk_mul_f32 v[176:177], v[0:1], v[176:177] op_sel_hi:[1,0]
	v_mul_f32_e32 v232, v248, v248
	v_mul_f32_e32 v244, v176, v176
	v_mul_f32_e32 v246, v177, v177
	v_mul_f32_e32 v238, v249, v249
	v_pk_add_f32 v[244:245], v[244:245], v[246:247]
	v_pk_add_f32 v[232:233], v[232:233], v[238:239]
	s_nop 0
	v_pk_add_f32 v[232:233], v[244:245], v[232:233]
	s_nop 0
	v_add_f32_e32 v232, v232, v233
	ds_bpermute_b32 v225, v225, v232
	s_waitcnt lgkmcnt(0)
	v_add_f32_e32 v225, v232, v225
	ds_bpermute_b32 v224, v224, v225
	v_lshlrev_b64 v[232:233], 10, v[156:157]
	v_lshl_add_u64 v[206:207], v[206:207], 0, v[232:233]
	s_waitcnt lgkmcnt(0)
	v_add_f32_e32 v224, v225, v224
	v_fmamk_f32 v224, v224, 0x3c800000, v210
	s_nop 0
	v_rsq_f32_e32 v224, v224
	s_nop 0
	v_mul_f32_e32 v224, v223, v224
	v_pk_mul_f32 v[228:229], v[228:229], v[224:225] op_sel_hi:[1,0]
	v_pk_mul_f32 v[230:231], v[230:231], v[224:225] op_sel_hi:[1,0]
	v_pk_mul_f32 v[140:141], v[140:141], v[228:229]
	v_pk_mul_f32 v[142:143], v[142:143], v[230:231]
	v_pk_mul_f32 v[228:229], v[234:235], v[224:225] op_sel_hi:[1,0]
	v_pk_mul_f32 v[230:231], v[236:237], v[224:225] op_sel_hi:[1,0]
	s_nop 0
	v_pk_mul_f32 v[230:231], v[138:139], v[230:231]
	v_pk_mul_f32 v[138:139], v[136:137], v[228:229]
	v_cvt_pk_bf16_f32 v136, v140, v141
	v_cvt_pk_bf16_f32 v137, v142, v143
	s_nop 0
	v_cvt_pk_bf16_f32 v138, v138, v139
	v_cvt_pk_bf16_f32 v139, v230, v231
	global_store_dwordx4 v[206:207], v[136:139], off
	s_nop 1
	v_pk_mul_f32 v[136:137], v[242:243], v[224:225] op_sel_hi:[1,0]
	v_pk_mul_f32 v[138:139], v[240:241], v[224:225] op_sel_hi:[1,0]
	v_pk_mul_f32 v[132:133], v[132:133], v[136:137]
	v_pk_mul_f32 v[134:135], v[134:135], v[138:139]
	v_pk_mul_f32 v[136:137], v[176:177], v[224:225] op_sel_hi:[1,0]
	v_pk_mul_f32 v[138:139], v[248:249], v[224:225] op_sel_hi:[1,0]
	s_nop 0
	v_pk_mul_f32 v[138:139], v[130:131], v[138:139]
	v_pk_mul_f32 v[130:131], v[128:129], v[136:137]
	v_cvt_pk_bf16_f32 v128, v132, v133
	v_cvt_pk_bf16_f32 v129, v134, v135
	s_nop 0
	v_cvt_pk_bf16_f32 v130, v130, v131
	v_cvt_pk_bf16_f32 v131, v138, v139
	s_nop 1
